# attention: end-of-item barrier moved to just before the next item's K->LDS writes (next item's K/Q loads issue without waiting for the slowest wave)
# baseline (speedup 1.0000x reference)
; __device__ __forceinline__ void phase_attn_items(const Params& P, LAS unsigned char* lds) {
;     ...
;     for (int it = 0; it < (xmap ? 6 : (3 * 512 + (int)gridDim.x - 1) / (int)gridDim.x); ++it) {
;     ...
;         if (h == 0) LseB[(size_t)pat * MTOK * 8 + qrow * 8 + hh] = (mx + __builtin_amdgcn_logf(sum)) * LN2F;
;         __syncthreads();
.LBB0_113:
	s_or_b64 exec, exec, s[24:25]
	v_readlane_b32 s72, v252, 40
	s_mov_b32 s2, 0
	v_readlane_b32 s73, v252, 41
	s_waitcnt lgkmcnt(0)
.LBB0_114:
	s_add_i32 s8, s8, 32
	s_add_i32 s7, s7, s62
	s_cmp_lg_u32 s2, 0
	s_cselect_b64 s[24:25], -1, 0

; #define LAS __attribute__((address_space(3)))
; __device__ __forceinline__ void phase_attn_items(const Params& P, LAS unsigned char* lds) {
;     ...
;         const int qt = 8 * ch8 + wave;
;         const size_t qrow = rowbase + ((size_t)(32 * qt + ql) << dlog) + r;
;         bf16x8 qf[8];
;         { const bf16_t* Qp = Q + qrow * AW + hh * 128 + 8 * h;
; #pragma unroll
;           for (int ks = 0; ks < 8; ++ks) qf[ks] = *(const bf16x8*)(Qp + 16 * ks); }
; #pragma unroll
;         for (int i = 0; i < 12; ++i) *(LAS u32x4*)(lds + i * 8192 + loff) = kk[i];
;         u32x4 vv[12];
; #pragma unroll
;         for (int i = 0; i < 12; ++i) { const int T = 8 * ch8 - 2 + i; if (T >= 0 && T < ntile) vv[i] = *(const u32x4*)(TILE_BASE(Vb, T) + roff); else vv[i] = (u32x4){0u, 0u, 0u, 0u}; }
.LBB0_150:
	v_readlane_b32 s30, v247, 13
	v_and_b32_e32 v165, 31, v174
	s_add_i32 s13, s13, s30
	v_lshl_or_b32 v50, s13, 5, v165
	v_ashrrev_i32_e32 v51, 31, v50
	v_lshlrev_b64 v[50:51], s98, v[50:51]
	v_lshl_add_u64 v[162:163], v[50:51], 0, s[42:43]
	v_readlane_b32 s72, v247, 3
	v_lshlrev_b64 v[50:51], 11, v[162:163]
	v_readlane_b32 s73, v247, 4
	v_ashrrev_i32_e32 v164, 5, v174
	v_lshlrev_b32_e32 v52, 3, v164
	v_lshl_add_u64 v[50:51], s[72:73], 0, v[50:51]
	s_lshl_b32 s72, s16, 7
	s_ashr_i32 s73, s72, 31
	v_lshl_add_u64 v[50:51], s[72:73], 1, v[50:51]
	v_ashrrev_i32_e32 v53, 31, v52
	v_lshl_add_u64 v[50:51], v[52:53], 1, v[50:51]
	global_load_dwordx4 v[158:161], v[50:51], off
	global_load_dwordx4 v[154:157], v[50:51], off offset:32
	global_load_dwordx4 v[150:153], v[50:51], off offset:64
	global_load_dwordx4 v[146:149], v[50:51], off offset:96
	global_load_dwordx4 v[142:145], v[50:51], off offset:128
	global_load_dwordx4 v[138:141], v[50:51], off offset:160
	global_load_dwordx4 v[134:137], v[50:51], off offset:192
	global_load_dwordx4 v[130:133], v[50:51], off offset:224
	v_readlane_b32 s30, v247, 7
	s_add_u32 s44, s30, s44
	v_readlane_b32 s30, v247, 8
	s_addc_u32 s45, s30, s45
	s_waitcnt vmcnt(0) lgkmcnt(0)
	s_barrier
	ds_write_b128 v169, v[6:9]
	ds_write_b128 v169, v[10:13] offset:8192
	ds_write_b128 v169, v[2:5] offset:16384
	ds_write_b128 v169, v[18:21] offset:24576
	ds_write_b128 v169, v[14:17] offset:32768
	ds_write_b128 v169, v[26:29] offset:40960
	ds_write_b128 v169, v[22:25] offset:49152
	ds_write_b128 v169, v[34:37] offset:57344
	ds_write_b128 v170, v[30:33]
	ds_write_b128 v171, v[42:45]
	ds_write_b128 v172, v[38:41]
	ds_write_b128 v173, v[46:49]
	v_lshl_add_u64 v[4:5], s[44:45], 0, v[0:1]
	s_and_b64 vcc, exec, s[40:41]
	v_mov_b32_e32 v83, 0
	v_mov_b32_e32 v84, 0
	v_mov_b32_e32 v85, 0
	s_cbranch_vccnz .LBB0_152
	s_lshl_b32 s30, s20, 5
	s_lshl_b64 s[44:45], s[30:31], s98
	s_add_u32 s44, s44, s42
	s_addc_u32 s45, s45, s43
	s_lshl_b64 s[44:45], s[44:45], 11
	v_lshl_add_u64 v[2:3], v[4:5], 0, s[44:45]
	global_load_dwordx4 v[82:85], v[2:3], off
